# v38 plus nt hint on the h1 row stores in mid phase (consumed only in the final phase)
# baseline (speedup 1.0000x reference)
; DI unsigned pk2(float lo, float hi) { const f32x2_t v = {lo, hi}; const bf16x2_t b = __builtin_convertvector(v, bf16x2_t); return __builtin_bit_cast(unsigned, b); }
; DI void mid_phase(const Params& p) {
;     ...
; #pragma unroll
;         for (int j = 0; j < 4; ++j) s += (y[j][0] * y[j][0] + y[j][1] * y[j][1]) + (y[j][2] * y[j][2] + y[j][3] * y[j][3]);
;         const float rs = rsqrtf(wave_sum(s) * (1.f / D) + EPS);
;         float s1 = 0.f;
; #pragma unroll
;         for (int j = 0; j < 4; ++j) { hv[j] = hv[j] + y[j] * rs * wpost[j]; s1 += (hv[j][0] * hv[j][0] + hv[j][1] * hv[j][1]) + (hv[j][2] * hv[j][2] + hv[j][3] * hv[j][3]); }
;         const float rs1 = rsqrtf(wave_sum(s1) * (1.f / D) + EPS);
;         u32x2* o = (u32x2*)(ws + OFF_ABUF + (size_t)r * D * 2);
; #pragma unroll
;         for (int j = 0; j < 4; ++j) { u32x2 w; w.x = pk2(hv[j][0] * rs1 * wpre[j][0], hv[j][1] * rs1 * wpre[j][1]); w.y = pk2(hv[j][2] * rs1 * wpre[j][2], hv[j][3] * rs1 * wpre[j][3]); o[lane + 64 * j] = w; }
.LBB0_630:
	s_or_b64 exec, exec, s[16:17]
	v_lshlrev_b32_e32 v105, 16, v95
	v_lshlrev_b32_e32 v104, 16, v94
	v_and_b32_e32 v95, 0xffff0000, v95
	v_and_b32_e32 v94, 0xffff0000, v94
	v_pk_mul_f32 v[112:113], v[94:95], v[94:95]
	v_lshlrev_b32_e32 v107, 16, v93
	v_lshlrev_b32_e32 v106, 16, v92
	v_and_b32_e32 v93, 0xffff0000, v93
	v_and_b32_e32 v92, 0xffff0000, v92
	v_pk_fma_f32 v[112:113], v[104:105], v[104:105], v[112:113]
	v_lshlrev_b32_e32 v108, 16, v90
	v_and_b32_e32 v109, 0xffff0000, v90
	v_lshlrev_b32_e32 v90, 16, v91
	v_lshlrev_b32_e32 v110, 16, v88
	v_pk_add_f32 v[112:113], v[112:113], v[112:113] op_sel_hi:[0,1]
	v_pk_mul_f32 v[114:115], v[92:93], v[92:93]
	v_and_b32_e32 v91, 0xffff0000, v91
	v_pk_fma_f32 v[114:115], v[106:107], v[106:107], v[114:115]
	v_mul_f32_e32 v111, v108, v108
	v_mul_f32_e32 v117, v109, v109
	v_mul_f32_e32 v112, v90, v90
	v_mov_b32_e32 v116, v110
	v_and_b32_e32 v79, 0xffff0000, v88
	v_lshlrev_b32_e32 v88, 16, v89
	v_and_b32_e32 v89, 0xffff0000, v89
	v_pk_add_f32 v[114:115], v[114:115], v[114:115] op_sel_hi:[0,1]
	v_pk_fma_f32 v[118:119], v[90:91], v[90:91], v[112:113] op_sel_hi:[1,1,0]
	v_pk_add_f32 v[116:117], v[110:111], v[116:117]
	v_mul_f32_e32 v118, v79, v79
	v_mul_f32_e32 v114, v88, v88
	v_mul_f32_e32 v112, v89, v89
	v_mul_f32_e32 v120, v110, v110
	v_mov_b32_e32 v121, v117
	v_pk_add_f32 v[116:117], v[120:121], v[118:119]
	v_pk_add_f32 v[112:113], v[114:115], v[112:113]
	v_mov_b32_e32 v114, v105
	v_pk_add_f32 v[112:113], v[116:117], v[112:113]
	v_mov_b32_e32 v115, v95
	v_add_f32_e32 v103, v112, v113
	ds_bpermute_b32 v111, v65, v103
	v_mov_b32_e32 v105, v94
	s_and_b64 s[0:1], exec, s[0:1]
	s_or_b64 s[14:15], s[0:1], s[14:15]
	s_waitcnt lgkmcnt(0)
	v_add_f32_e32 v103, v103, v111
	ds_bpermute_b32 v111, v96, v103
	s_waitcnt lgkmcnt(0)
	v_add_f32_e32 v103, v103, v111
	ds_bpermute_b32 v111, v97, v103
	s_waitcnt lgkmcnt(0)
	v_add_f32_e32 v103, v103, v111
	ds_bpermute_b32 v111, v98, v103
	s_waitcnt lgkmcnt(0)
	v_add_f32_e32 v103, v103, v111
	ds_bpermute_b32 v111, v99, v103
	s_waitcnt lgkmcnt(0)
	v_add_f32_e32 v103, v103, v111
	ds_bpermute_b32 v111, v100, v103
	s_waitcnt lgkmcnt(0)
	v_add_f32_e32 v103, v103, v111
	v_fmamk_f32 v103, v103, 0x3a800000, v102
	v_mul_f32_e32 v111, 0x4b800000, v103
	v_cmp_gt_f32_e32 vcc, s37, v103
	s_nop 1
	v_cndmask_b32_e32 v103, v103, v111, vcc
	v_rsq_f32_e32 v103, v103
	s_nop 0
	v_mul_f32_e32 v111, 0x45800000, v103
	v_cndmask_b32_e32 v112, v103, v111, vcc
	v_pk_mul_f32 v[114:115], v[112:113], v[114:115] op_sel_hi:[0,1]
	v_pk_mul_f32 v[94:95], v[112:113], v[104:105] op_sel_hi:[0,1]
	v_pk_fma_f32 v[52:53], v[4:5], v[94:95], v[52:53]
	v_pk_fma_f32 v[54:55], v[6:7], v[114:115], v[54:55]
	v_pk_mul_f32 v[104:105], v[52:53], v[52:53]
	v_pk_mul_f32 v[94:95], v[54:55], v[54:55]
	v_pk_mul_f32 v[90:91], v[90:91], v[112:113] op_sel_hi:[1,0]
	v_pk_mov_b32 v[114:115], v[104:105], v[94:95] op_sel:[1,0]
	v_mov_b32_e32 v105, v95
	v_pk_add_f32 v[94:95], v[114:115], v[104:105]
	v_mov_b32_e32 v104, v107
	v_mov_b32_e32 v105, v93
	v_mov_b32_e32 v107, v92
	v_pk_mul_f32 v[104:105], v[112:113], v[104:105] op_sel_hi:[0,1]
	v_pk_mul_f32 v[92:93], v[112:113], v[106:107] op_sel_hi:[0,1]
	v_pk_fma_f32 v[40:41], v[8:9], v[92:93], v[40:41]
	v_pk_fma_f32 v[42:43], v[10:11], v[104:105], v[42:43]
	v_pk_mul_f32 v[104:105], v[40:41], v[40:41]
	v_pk_mul_f32 v[92:93], v[42:43], v[42:43]
	v_pk_fma_f32 v[38:39], v[22:23], v[90:91], v[38:39]
	v_pk_mov_b32 v[106:107], v[104:105], v[92:93] op_sel:[1,0]
	v_mov_b32_e32 v105, v93
	v_pk_add_f32 v[92:93], v[106:107], v[104:105]
	v_pk_mul_f32 v[104:105], v[108:109], v[112:113] op_sel_hi:[1,0]
	v_mov_b32_e32 v111, v79
	v_pk_fma_f32 v[36:37], v[20:21], v[104:105], v[36:37]
	v_pk_mul_f32 v[106:107], v[110:111], v[112:113] op_sel_hi:[1,0]
	v_mul_f32_e32 v90, v36, v36
	v_pk_fma_f32 v[90:91], v[36:37], v[36:37], v[90:91] op_sel_hi:[1,1,0]
	v_pk_mul_f32 v[88:89], v[88:89], v[112:113] op_sel_hi:[1,0]
	v_mul_f32_e32 v90, v38, v38
	v_pk_add_f32 v[94:95], v[94:95], v[94:95] op_sel_hi:[0,1]
	v_pk_add_f32 v[92:93], v[92:93], v[92:93] op_sel_hi:[0,1]
	v_pk_fma_f32 v[104:105], v[38:39], v[38:39], v[90:91] op_sel_hi:[1,1,0]
	v_pk_fma_f32 v[34:35], v[26:27], v[88:89], v[34:35]
	v_pk_fma_f32 v[32:33], v[24:25], v[106:107], v[32:33]
	v_mul_f32_e32 v94, v34, v34
	v_mul_f32_e32 v90, v32, v32
	v_mul_f32_e32 v104, v33, v33
	v_mul_f32_e32 v92, v35, v35
	v_pk_add_f32 v[88:89], v[90:91], v[104:105]
	v_pk_add_f32 v[90:91], v[94:95], v[92:93]
	s_nop 0
	v_pk_add_f32 v[88:89], v[88:89], v[90:91]
	s_nop 0
	v_add_f32_e32 v79, v88, v89
	ds_bpermute_b32 v88, v65, v79
	s_waitcnt lgkmcnt(0)
	v_add_f32_e32 v79, v79, v88
	ds_bpermute_b32 v88, v96, v79
	s_waitcnt lgkmcnt(0)
	v_add_f32_e32 v79, v79, v88
	ds_bpermute_b32 v88, v97, v79
	s_waitcnt lgkmcnt(0)
	v_add_f32_e32 v79, v79, v88
	ds_bpermute_b32 v88, v98, v79
	s_waitcnt lgkmcnt(0)
	v_add_f32_e32 v79, v79, v88
	ds_bpermute_b32 v88, v99, v79
	s_waitcnt lgkmcnt(0)
	v_add_f32_e32 v79, v79, v88
	ds_bpermute_b32 v88, v100, v79
	s_waitcnt lgkmcnt(0)
	v_add_f32_e32 v79, v79, v88
	v_fmamk_f32 v79, v79, 0x3a800000, v102
	v_mul_f32_e32 v88, 0x4b800000, v79
	v_cmp_gt_f32_e32 vcc, s37, v79
	s_nop 1
	v_cndmask_b32_e32 v79, v79, v88, vcc
	v_rsq_f32_e32 v79, v79
	s_nop 0
	v_mul_f32_e32 v88, 0x45800000, v79
	v_cndmask_b32_e32 v88, v79, v88, vcc
	v_pk_mul_f32 v[90:91], v[52:53], v[88:89] op_sel_hi:[1,0]
	v_pk_mul_f32 v[92:93], v[54:55], v[88:89] op_sel_hi:[1,0]
	v_pk_mul_f32 v[90:91], v[0:1], v[90:91]
	v_pk_mul_f32 v[92:93], v[2:3], v[92:93]
	v_cvt_pk_bf16_f32 v90, v90, v91
	v_cvt_pk_bf16_f32 v91, v92, v93
	v_lshl_add_u64 v[92:93], v[72:73], 0, v[70:71]
	v_add_co_u32_e32 v92, vcc, s40, v92
	v_pk_mul_f32 v[94:95], v[42:43], v[88:89] op_sel_hi:[1,0]
	s_nop 0
	v_addc_co_u32_e32 v93, vcc, 0, v93, vcc
	global_store_dwordx2 v[92:93], v[90:91], off
	v_pk_mul_f32 v[90:91], v[40:41], v[88:89] op_sel_hi:[1,0]
	v_pk_mul_f32 v[94:95], v[14:15], v[94:95]
	v_pk_mul_f32 v[90:91], v[12:13], v[90:91]
	v_cmp_lt_u32_e32 vcc, 15, v69
	v_cvt_pk_bf16_f32 v90, v90, v91
	v_cvt_pk_bf16_f32 v91, v94, v95
	global_store_dwordx2 v[92:93], v[90:91], off offset:512
	v_pk_mul_f32 v[90:91], v[36:37], v[88:89] op_sel_hi:[1,0]
	v_pk_mul_f32 v[94:95], v[38:39], v[88:89] op_sel_hi:[1,0]
	v_pk_mul_f32 v[90:91], v[16:17], v[90:91]
	v_pk_mul_f32 v[94:95], v[18:19], v[94:95]
	v_cvt_pk_bf16_f32 v90, v90, v91
	v_cvt_pk_bf16_f32 v91, v94, v95
	global_store_dwordx2 v[92:93], v[90:91], off offset:1024
	v_pk_mul_f32 v[90:91], v[32:33], v[88:89] op_sel_hi:[1,0]
	v_pk_mul_f32 v[88:89], v[34:35], v[88:89] op_sel_hi:[1,0]
	v_pk_mul_f32 v[90:91], v[28:29], v[90:91]
	v_pk_mul_f32 v[88:89], v[30:31], v[88:89]
	v_cvt_pk_bf16_f32 v90, v90, v91
	v_cvt_pk_bf16_f32 v91, v88, v89
	global_store_dwordx2 v[92:93], v[90:91], off offset:1536
	s_and_saveexec_b64 s[0:1], vcc
	s_cbranch_execz .LBB0_621
; DI unsigned pk2(float lo, float hi) { const f32x2_t v = {lo, hi}; const bf16x2_t b = __builtin_convertvector(v, bf16x2_t); return __builtin_bit_cast(unsigned, b); }
; DI void mid_phase(const Params& p) {
;     ...
;         if (l >= NMETA) { u32x2* hrow = (u32x2*)(ws + OFF_H1 + ((size_t)b * SEQ + (l - NMETA)) * D * 2);
; #pragma unroll
;             for (int j = 0; j < 4; ++j) { u32x2 hw; hw.x = pk2(hv[j][0], hv[j][1]); hw.y = pk2(hv[j][2], hv[j][3]); hrow[lane + 64 * j] = hw; } }
	v_ashrrev_i32_e32 v79, 31, v78
	v_add_u32_e32 v88, -16, v69
	v_mov_b32_e32 v89, v67
	v_lshlrev_b64 v[78:79], 23, v[78:79]
	v_lshlrev_b64 v[88:89], 11, v[88:89]
	v_lshl_add_u64 v[78:79], s[6:7], 0, v[78:79]
	v_lshl_add_u64 v[78:79], v[78:79], 0, v[88:89]
	v_mov_b32_e32 v69, v67
	v_cvt_pk_bf16_f32 v52, v52, v53
	v_cvt_pk_bf16_f32 v53, v54, v55
	v_lshl_add_u64 v[54:55], v[78:79], 0, v[68:69]
	v_cvt_pk_bf16_f32 v40, v40, v41
	v_cvt_pk_bf16_f32 v41, v42, v43
	v_cvt_pk_bf16_f32 v36, v36, v37
	v_cvt_pk_bf16_f32 v37, v38, v39
	v_cvt_pk_bf16_f32 v32, v32, v33
	v_cvt_pk_bf16_f32 v33, v34, v35
	global_store_dwordx2 v[54:55], v[52:53], off nt
	global_store_dwordx2 v[54:55], v[40:41], off offset:512 nt
	global_store_dwordx2 v[54:55], v[36:37], off offset:1024 nt
	global_store_dwordx2 v[54:55], v[32:33], off offset:1536 nt
	s_branch .LBB0_621
